# v43: P6 per-chunk token sum-of-squares exchange via v_permlane32_swap instead of ds_bpermute (2 LDS round trips per chunk removed)
# speedup vs baseline: 1.0012x; 1.0012x over previous
; template <bool FULL, bool PARTIAL  > ...
;     ...
;             for (int kb = 0; kb < 4; ++kb) {
; #pragma unroll
;                 for (int s2 = 0; s2 < 2; ++s2) {
;                     u32x4 sw; sw.x = cvtpk(Sacc[kb][8 * s2 + 0], Sacc[kb][8 * s2 + 1]); sw.y = cvtpk(Sacc[kb][8 * s2 + 2], Sacc[kb][8 * s2 + 3]);
;                     sw.z = cvtpk(Sacc[kb][8 * s2 + 4], Sacc[kb][8 * s2 + 5]); sw.w = cvtpk(Sacc[kb][8 * s2 + 6], Sacc[kb][8 * s2 + 7]);
;                     const bf16x8 sb = __builtin_bit_cast(bf16x8, sw);
; #pragma unroll
;                     for (int tb = 0; tb < 2; ++tb) {
;                         const LAS bf16_t* qp = qt_r4 + (32 * tb) * QST + 32 * kb + 16 * s2;
;                         const s16x4 lo = *(const LAS s16x4*)qp, hi = *(const LAS s16x4*)(qp + 8);
;                         const bf16x8 qa = __builtin_shufflevector(lo, hi, 0, 1, 2, 3, 4, 5, 6, 7);
;                         oT[tb] = MFMA32(sb, qa, oT[tb]);
;                     }
;                 }
;                 __builtin_amdgcn_sched_barrier(0);
;             }
;             __syncthreads();
;             {
;                 const LAS bf16_t* vt_r = opq(VS + (8 * h + ((lane & 15) >> 2)) * VST + 32 * w + 16 * ((lane >> 4) & 1) + 4 * (lane & 3));
; #pragma unroll
;                 for (int s4 = 0; s4 < 4; ++s4) { const s16x4 vlo = tr16(vt_r + (16 * s4) * VST), vhi = tr16(vt_r + (16 * s4 + 4) * VST); vfr[s4] = __builtin_shufflevector(vlo, vhi, 0, 1, 2, 3, 4, 5, 6, 7); }
;             }
; #pragma unroll
;             for (int tb = 0; tb < 2; ++tb)
; #pragma unroll
;                 for (int q4 = 0; q4 < 4; ++q4) grv[tb][q4] = *(const u32x2*)(AB + (size_t)crow0 * 2048 + hd * 256 + 32 * w + 8 * q4 + (unsigned)(min(32 * tb + r, nv1) * 2048 + 4 * h));
;             const LAS bf16_t* ab_r = opq(Ab + r * TST + 8 * h);
; #pragma unroll
;             for (int tb = 0; tb < 2; ++tb)
; #pragma unroll
;                 for (int sb = 0; sb < 2; ++sb) {
;                     if (sb > tb) continue;
; #pragma unroll
;                     for (int s2 = 0; s2 < 2; ++s2) {
;                         const bf16x8 aa = *(const LAS bf16x8*)(ab_r + (32 * tb) * TST + 32 * sb + 16 * s2);
;                         oT[tb] = MFMA32(vfr[2 * sb + s2], aa, oT[tb]);
;                     }
;                 }
;         }
;         const LAS bf16_t* kdt_r = opq(KdT + r * TST + 8 * h);
;         if (!FULL) {
.LBB0_1324:
	v_mov_b32_e32 v2, v225
	v_cvt_pk_bf16_f32 v4, v18, v19
	v_cvt_pk_bf16_f32 v5, v20, v21
	v_cvt_pk_bf16_f32 v6, v22, v23
	v_cvt_pk_bf16_f32 v7, v24, v25
	ds_read2_b64 v[8:11], v2 offset1:2
	v_add_u32_e32 v150, 0x2000, v2
	s_waitcnt lgkmcnt(0)
	v_mfma_f32_32x32x16_bf16 v[114:129], v[4:7], v[8:11], 0
	ds_read2_b64 v[8:11], v150 offset0:64 offset1:66
	ds_read2_b64 v[12:15], v2 offset0:4 offset1:6
	s_waitcnt lgkmcnt(1)
	v_mfma_f32_32x32x16_bf16 v[98:113], v[4:7], v[8:11], 0
	v_cvt_pk_bf16_f32 v4, v26, v27
	v_cvt_pk_bf16_f32 v5, v28, v29
	v_cvt_pk_bf16_f32 v6, v30, v31
	v_cvt_pk_bf16_f32 v7, v32, v33
	ds_read2_b64 v[8:11], v150 offset0:68 offset1:70
	s_waitcnt lgkmcnt(1)
	v_mfma_f32_32x32x16_bf16 v[114:129], v[4:7], v[12:15], v[114:129]
	s_waitcnt lgkmcnt(0)
	v_mfma_f32_32x32x16_bf16 v[98:113], v[4:7], v[8:11], v[98:113]
	v_cvt_pk_bf16_f32 v4, v34, v35
	v_cvt_pk_bf16_f32 v5, v36, v37
	v_cvt_pk_bf16_f32 v6, v38, v39
	v_cvt_pk_bf16_f32 v7, v40, v41
	ds_read2_b64 v[8:11], v2 offset0:8 offset1:10
	s_waitcnt lgkmcnt(0)
	v_mfma_f32_32x32x16_bf16 v[114:129], v[4:7], v[8:11], v[114:129]
	ds_read2_b64 v[8:11], v150 offset0:72 offset1:74
	ds_read2_b64 v[12:15], v2 offset0:12 offset1:14
	s_waitcnt lgkmcnt(1)
	v_mfma_f32_32x32x16_bf16 v[98:113], v[4:7], v[8:11], v[98:113]
	v_cvt_pk_bf16_f32 v4, v42, v43
	v_cvt_pk_bf16_f32 v5, v44, v45
	v_cvt_pk_bf16_f32 v6, v46, v47
	v_cvt_pk_bf16_f32 v7, v48, v49
	ds_read2_b64 v[8:11], v150 offset0:76 offset1:78
	s_waitcnt lgkmcnt(1)
	v_mfma_f32_32x32x16_bf16 v[114:129], v[4:7], v[12:15], v[114:129]
	s_waitcnt lgkmcnt(0)
	v_mfma_f32_32x32x16_bf16 v[98:113], v[4:7], v[8:11], v[98:113]
	v_cvt_pk_bf16_f32 v4, v50, v51
	v_cvt_pk_bf16_f32 v5, v52, v53
	v_cvt_pk_bf16_f32 v6, v54, v55
	v_cvt_pk_bf16_f32 v7, v56, v57
	ds_read2_b64 v[8:11], v2 offset0:16 offset1:18
	s_waitcnt lgkmcnt(0)
	v_mfma_f32_32x32x16_bf16 v[114:129], v[4:7], v[8:11], v[114:129]
	ds_read2_b64 v[8:11], v150 offset0:80 offset1:82
	ds_read2_b64 v[12:15], v2 offset0:20 offset1:22
	s_waitcnt lgkmcnt(1)
	v_mfma_f32_32x32x16_bf16 v[98:113], v[4:7], v[8:11], v[98:113]
	v_cvt_pk_bf16_f32 v4, v58, v59
	v_cvt_pk_bf16_f32 v5, v60, v61
	v_cvt_pk_bf16_f32 v6, v62, v63
	v_cvt_pk_bf16_f32 v7, v64, v65
	ds_read2_b64 v[8:11], v150 offset0:84 offset1:86
	s_waitcnt lgkmcnt(1)
	v_mfma_f32_32x32x16_bf16 v[114:129], v[4:7], v[12:15], v[114:129]
	s_waitcnt lgkmcnt(0)
	v_mfma_f32_32x32x16_bf16 v[98:113], v[4:7], v[8:11], v[98:113]
	v_cvt_pk_bf16_f32 v4, v66, v67
	v_cvt_pk_bf16_f32 v5, v68, v69
	v_cvt_pk_bf16_f32 v6, v70, v71
	v_cvt_pk_bf16_f32 v7, v72, v73
	ds_read2_b64 v[8:11], v2 offset0:24 offset1:26
	s_waitcnt lgkmcnt(0)
	v_mfma_f32_32x32x16_bf16 v[114:129], v[4:7], v[8:11], v[114:129]
	ds_read2_b64 v[8:11], v150 offset0:88 offset1:90
	ds_read2_b64 v[12:15], v2 offset0:28 offset1:30
	s_waitcnt lgkmcnt(1)
	v_mfma_f32_32x32x16_bf16 v[98:113], v[4:7], v[8:11], v[98:113]
	v_cvt_pk_bf16_f32 v4, v74, v75
	v_cvt_pk_bf16_f32 v5, v76, v77
	v_cvt_pk_bf16_f32 v6, v78, v79
	v_cvt_pk_bf16_f32 v7, v80, v81
	ds_read2_b64 v[8:11], v150 offset0:92 offset1:94
	s_waitcnt lgkmcnt(1)
	v_mfma_f32_32x32x16_bf16 v[114:129], v[4:7], v[12:15], v[114:129]
	s_waitcnt lgkmcnt(0)
	v_mfma_f32_32x32x16_bf16 v[98:113], v[4:7], v[8:11], v[98:113]
	v_lshl_add_u64 v[156:157], v[178:179], 0, s[60:61]
	s_mov_b32 s72, 0xa800000
	v_add_co_u32_e32 v158, vcc, s72, v156
	s_mov_b32 s72, 0xa820000
	s_nop 0
	v_addc_co_u32_e32 v159, vcc, 0, v157, vcc
	v_mov_b32_e32 v2, v245
	v_add_co_u32_e32 v156, vcc, s72, v156
	s_barrier
	s_nop 0
	v_addc_co_u32_e32 v157, vcc, 0, v157, vcc
	ds_read_b64_tr_b16 v[4:5], v2
	ds_read_b64_tr_b16 v[6:7], v2 offset:2304
	ds_read_b64_tr_b16 v[12:13], v2 offset:9216
	ds_read_b64_tr_b16 v[14:15], v2 offset:11520
	ds_read_b64_tr_b16 v[150:151], v2 offset:18432
	ds_read_b64_tr_b16 v[152:153], v2 offset:20736
	ds_read_b64_tr_b16 v[8:9], v2 offset:27648
	ds_read_b64_tr_b16 v[10:11], v2 offset:29952
	global_load_dwordx2 v[194:195], v[158:159], off
	global_load_dwordx2 v[192:193], v[158:159], off offset:16
	global_load_dwordx2 v[190:191], v[158:159], off offset:32
	global_load_dwordx2 v[188:189], v[158:159], off offset:48
	global_load_dwordx2 v[186:187], v[156:157], off
	global_load_dwordx2 v[184:185], v[156:157], off offset:16
	global_load_dwordx2 v[182:183], v[156:157], off offset:32
	global_load_dwordx2 v[180:181], v[156:157], off offset:48
	v_mov_b32_e32 v2, v227
	ds_read_b128 v[156:159], v2
	ds_read_b128 v[200:203], v2 offset:32
	s_waitcnt lgkmcnt(1)
	v_mfma_f32_32x32x16_bf16 v[114:129], v[4:7], v[156:159], v[114:129]
	ds_read_b128 v[156:159], v2 offset:4608
	v_mov_b32_e32 v155, v229
	s_waitcnt lgkmcnt(0)
	v_mfma_f32_32x32x16_bf16 v[98:113], v[4:7], v[156:159], v[98:113]
	ds_read_b128 v[156:159], v2 offset:4640
	s_waitcnt lgkmcnt(0)
	v_mfma_f32_32x32x16_bf16 v[98:113], v[12:15], v[156:159], v[98:113]
	ds_read_b128 v[156:159], v2 offset:4672
	s_waitcnt lgkmcnt(0)
	v_mfma_f32_32x32x16_bf16 v[98:113], v[150:153], v[156:159], v[98:113]
	ds_read_b128 v[156:159], v2 offset:4704
	v_mov_b32_e32 v2, v228
	v_mfma_f32_32x32x16_bf16 v[114:129], v[12:15], v[200:203], v[114:129]
	s_waitcnt lgkmcnt(0)
	v_mfma_f32_32x32x16_bf16 v[98:113], v[8:11], v[156:159], v[98:113]
	ds_read_b128 v[156:159], v155
	ds_read_b128 v[200:203], v155 offset:32
	ds_read_b128 v[204:207], v155 offset:64
	ds_read_b128 v[208:211], v155 offset:96
	s_waitcnt lgkmcnt(3)
	v_pk_mul_f32 v[20:21], v[20:21], v[158:159]
	s_waitcnt lgkmcnt(2)
	v_pk_mul_f32 v[24:25], v[24:25], v[202:203]
	v_pk_mul_f32 v[22:23], v[22:23], v[200:201]
	v_pk_mul_f32 v[18:19], v[18:19], v[156:157]
	ds_read_b128 v[156:159], v2
	ds_read_b128 v[200:203], v2 offset:32
	s_waitcnt lgkmcnt(2)
; #define LAS __attribute__((address_space(3)))
; #define MFMA32(a, b, c) __builtin_amdgcn_mfma_f32_32x32x16_bf16((a), (b), (c), 0, 0, 0)
; template <bool FULL, bool PARTIAL  > ...
;     ...
;         for (int kb = 0; kb < 4; ++kb) {
; #pragma unroll
;             for (int q4 = 0; q4 < 4; ++q4) { const f32x4 e = *(const LAS f32x4*)(eb_r + 32 * kb + 8 * q4);
; #pragma unroll
;                 for (int e2 = 0; e2 < 4; ++e2) Sacc[kb][4 * q4 + e2] *= e[e2]; }
; #pragma unroll
;             for (int s = 0; s < 4; ++s) {
;                 const bf16x8 ka = *(const LAS bf16x8*)(kdt_r + (32 * kb) * TST + 16 * s);
;                 Sacc[kb] = MFMA32(ka, vfr[s], Sacc[kb]);
;             }
;             __builtin_amdgcn_sched_barrier(0);
;         }
;         if (FULL) {
; #pragma unroll
;             for (int tb = 0; tb < 2; ++tb) { float p = 0.f;
; #pragma unroll
;                 for (int i = 0; i < 16; ++i) p += oT[tb][i] * oT[tb][i];
;                 p += __shfl_xor(p, 32);
;                 if (h == 0) part_p[w * 64 + 32 * tb] = p; }
	v_pk_mul_f32 v[32:33], v[32:33], v[210:211]
	v_pk_mul_f32 v[28:29], v[28:29], v[206:207]
	v_pk_mul_f32 v[30:31], v[30:31], v[208:209]
	v_pk_mul_f32 v[26:27], v[26:27], v[204:205]
	s_waitcnt lgkmcnt(1)
	s_nop 0
	v_mfma_f32_32x32x16_bf16 v[18:33], v[156:159], v[4:7], v[18:33]
	ds_read_b128 v[156:159], v2 offset:64
	s_waitcnt lgkmcnt(1)
	v_mfma_f32_32x32x16_bf16 v[18:33], v[200:203], v[12:15], v[18:33]
	s_waitcnt lgkmcnt(0)
	v_mfma_f32_32x32x16_bf16 v[18:33], v[156:159], v[150:153], v[18:33]
	ds_read_b128 v[156:159], v2 offset:96
	s_waitcnt lgkmcnt(0)
	v_mfma_f32_32x32x16_bf16 v[18:33], v[156:159], v[8:11], v[18:33]
	ds_read_b128 v[156:159], v155 offset:128
	ds_read_b128 v[200:203], v155 offset:160
	ds_read_b128 v[204:207], v155 offset:192
	ds_read_b128 v[208:211], v155 offset:224
	s_waitcnt lgkmcnt(3)
	v_pk_mul_f32 v[36:37], v[36:37], v[158:159]
	s_waitcnt lgkmcnt(2)
	v_pk_mul_f32 v[40:41], v[40:41], v[202:203]
	v_pk_mul_f32 v[38:39], v[38:39], v[200:201]
	v_pk_mul_f32 v[34:35], v[34:35], v[156:157]
	ds_read_b128 v[156:159], v2 offset:4608
	ds_read_b128 v[200:203], v2 offset:4640
	s_waitcnt lgkmcnt(2)
	v_pk_mul_f32 v[48:49], v[48:49], v[210:211]
	v_pk_mul_f32 v[44:45], v[44:45], v[206:207]
	v_pk_mul_f32 v[46:47], v[46:47], v[208:209]
	v_pk_mul_f32 v[42:43], v[42:43], v[204:205]
	s_waitcnt lgkmcnt(1)
	s_nop 0
	v_mfma_f32_32x32x16_bf16 v[34:49], v[156:159], v[4:7], v[34:49]
	ds_read_b128 v[156:159], v2 offset:4672
	s_waitcnt lgkmcnt(1)
	v_mfma_f32_32x32x16_bf16 v[34:49], v[200:203], v[12:15], v[34:49]
	s_waitcnt lgkmcnt(0)
	v_mfma_f32_32x32x16_bf16 v[34:49], v[156:159], v[150:153], v[34:49]
	ds_read_b128 v[156:159], v2 offset:4704
	s_waitcnt lgkmcnt(0)
	v_mfma_f32_32x32x16_bf16 v[34:49], v[156:159], v[8:11], v[34:49]
	ds_read_b128 v[156:159], v155 offset:256
	ds_read_b128 v[200:203], v155 offset:288
	ds_read_b128 v[204:207], v155 offset:320
	ds_read_b128 v[208:211], v155 offset:352
	s_waitcnt lgkmcnt(3)
	v_pk_mul_f32 v[52:53], v[52:53], v[158:159]
	s_waitcnt lgkmcnt(2)
	v_pk_mul_f32 v[56:57], v[56:57], v[202:203]
	v_pk_mul_f32 v[54:55], v[54:55], v[200:201]
	v_pk_mul_f32 v[50:51], v[50:51], v[156:157]
	ds_read_b128 v[156:159], v2 offset:9216
	ds_read_b128 v[200:203], v2 offset:9248
	s_waitcnt lgkmcnt(2)
	v_pk_mul_f32 v[64:65], v[64:65], v[210:211]
	v_pk_mul_f32 v[60:61], v[60:61], v[206:207]
	v_pk_mul_f32 v[62:63], v[62:63], v[208:209]
	v_pk_mul_f32 v[58:59], v[58:59], v[204:205]
	s_waitcnt lgkmcnt(1)
	s_nop 0
	v_mfma_f32_32x32x16_bf16 v[50:65], v[156:159], v[4:7], v[50:65]
	ds_read_b128 v[156:159], v2 offset:9280
	s_waitcnt lgkmcnt(1)
	v_mfma_f32_32x32x16_bf16 v[50:65], v[200:203], v[12:15], v[50:65]
	s_waitcnt lgkmcnt(0)
	v_mfma_f32_32x32x16_bf16 v[50:65], v[156:159], v[150:153], v[50:65]
	ds_read_b128 v[156:159], v2 offset:9312
	s_waitcnt lgkmcnt(0)
	v_mfma_f32_32x32x16_bf16 v[50:65], v[156:159], v[8:11], v[50:65]
	ds_read_b128 v[156:159], v155 offset:384
	ds_read_b128 v[200:203], v155 offset:416
	ds_read_b128 v[204:207], v155 offset:448
	ds_read_b128 v[208:211], v155 offset:480
	s_waitcnt lgkmcnt(3)
	v_pk_mul_f32 v[68:69], v[68:69], v[158:159]
	s_waitcnt lgkmcnt(2)
	v_pk_mul_f32 v[72:73], v[72:73], v[202:203]
	v_pk_mul_f32 v[70:71], v[70:71], v[200:201]
	v_pk_mul_f32 v[66:67], v[66:67], v[156:157]
	ds_read_b128 v[156:159], v2 offset:13824
	ds_read_b128 v[200:203], v2 offset:13856
	s_waitcnt lgkmcnt(2)
	v_pk_mul_f32 v[80:81], v[80:81], v[210:211]
	v_pk_mul_f32 v[76:77], v[76:77], v[206:207]
	v_pk_mul_f32 v[78:79], v[78:79], v[208:209]
	v_pk_mul_f32 v[74:75], v[74:75], v[204:205]
	s_waitcnt lgkmcnt(1)
	s_nop 0
	v_mfma_f32_32x32x16_bf16 v[66:81], v[156:159], v[4:7], v[66:81]
	ds_read_b128 v[4:7], v2 offset:13888
	s_waitcnt lgkmcnt(1)
	v_mfma_f32_32x32x16_bf16 v[66:81], v[200:203], v[12:15], v[66:81]
	s_waitcnt lgkmcnt(0)
	v_mfma_f32_32x32x16_bf16 v[66:81], v[4:7], v[150:153], v[66:81]
	ds_read_b128 v[4:7], v2 offset:13920
	s_waitcnt lgkmcnt(0)
	v_mfma_f32_32x32x16_bf16 v[66:81], v[4:7], v[8:11], v[66:81]
	v_mul_f32_e32 v2, v115, v115
	v_fmac_f32_e32 v2, v114, v114
	v_fmac_f32_e32 v2, v116, v116
	v_fmac_f32_e32 v2, v117, v117
	v_fmac_f32_e32 v2, v118, v118
	v_fmac_f32_e32 v2, v119, v119
	v_fmac_f32_e32 v2, v120, v120
	v_fmac_f32_e32 v2, v121, v121
	v_fmac_f32_e32 v2, v122, v122
	v_fmac_f32_e32 v2, v123, v123
	v_fmac_f32_e32 v2, v124, v124
	v_fmac_f32_e32 v2, v125, v125
	v_fmac_f32_e32 v2, v126, v126
	v_fmac_f32_e32 v2, v127, v127
	v_fmac_f32_e32 v2, v128, v128
	v_fmac_f32_e32 v2, v129, v129
	v_mov_b32_e32 v4, v2
	s_nop 1
	v_permlane32_swap_b32_e32 v2, v4
	s_and_saveexec_b64 s[72:73], s[4:5]
	s_cbranch_execz .LBB0_1326
	s_waitcnt lgkmcnt(0)
	v_add_f32_e32 v2, v2, v4
	ds_write_b32 v246, v2
.LBB0_1326:
	s_or_b64 exec, exec, s[72:73]
	v_mul_f32_e32 v2, v99, v99
	v_fmac_f32_e32 v2, v98, v98
	v_fmac_f32_e32 v2, v100, v100
	v_fmac_f32_e32 v2, v101, v101
	v_fmac_f32_e32 v2, v102, v102
	v_fmac_f32_e32 v2, v103, v103
	v_fmac_f32_e32 v2, v104, v104
	v_fmac_f32_e32 v2, v105, v105
	v_fmac_f32_e32 v2, v106, v106
	v_fmac_f32_e32 v2, v107, v107
	v_fmac_f32_e32 v2, v108, v108
	v_fmac_f32_e32 v2, v109, v109
	v_fmac_f32_e32 v2, v110, v110
	v_fmac_f32_e32 v2, v111, v111
	v_fmac_f32_e32 v2, v112, v112
	v_fmac_f32_e32 v2, v113, v113
	s_waitcnt lgkmcnt(0)
	v_mov_b32_e32 v4, v2
	s_nop 1
	v_permlane32_swap_b32_e32 v2, v4
	s_and_saveexec_b64 s[72:73], s[4:5]
	s_cbranch_execz .LBB0_1311
	s_waitcnt lgkmcnt(0)
	v_add_f32_e32 v2, v2, v4
	ds_write_b32 v246, v2 offset:128
	s_branch .LBB0_1311
